# MLA loop: next tile's global K/V prefetch issued in the wait states behind the last QK MFMA (replaces the idle pad), nothing between the barrier and the K fragment reads
# speedup vs baseline: 1.0060x; 1.0042x over previous
; #define MFMA(a, b, c) __builtin_amdgcn_mfma_f32_32x32x16_bf16((a), (b), (c), 0, 0, 0)
; DI float xhalf_max(float x) { const auto rr = __builtin_amdgcn_permlane32_swap(__float_as_uint(x), __float_as_uint(x), false, false); return fmaxf(__uint_as_float(rr[0]), __uint_as_float(rr[1])); }
; DI float xhalf_sum(float x) { const auto rr = __builtin_amdgcn_permlane32_swap(__float_as_uint(x), __float_as_uint(x), false, false); return __uint_as_float(rr[0]) + __uint_as_float(rr[1]); }
; template <int DQK, int DV, bool BAND> ...
;     ...
;     if (PREF && kt + 1 < kt_hi) ALOAD(kt + 1);
;     if constexpr (DQK < 128) {
;       f32x16 p0, p1;
; #pragma unroll
;       for (int r = 0; r < 16; ++r) { p0[r] = 0.f; p1[r] = 0.f; }
;       __builtin_amdgcn_s_setprio(1);
; #pragma unroll
;       for (int d0 = 0; d0 < ND0; ++d0) {
;         const bf16x8 k0f = *(const bf16x8*)&Ks[r32 * KLD + d0 * 16 + hi * 8];
;         const bf16x8 k1f = *(const bf16x8*)&Ks[(32 + r32) * KLD + d0 * 16 + hi * 8];
;         p0 = MFMA(k0f, qf[d0], p0); p1 = MFMA(k1f, qf[d0], p1);
;       }
;       __builtin_amdgcn_s_setprio(0);
;       float mx = fmaxf(p0[0], p1[0]);
; #pragma unroll
;       for (int r = 1; r < 16; ++r) mx = fmaxf(mx, fmaxf(p0[r], p1[r]));
;       mx = xhalf_max(mx);
;       if (__builtin_amdgcn_ballot_w64(mx > m_run + 8.f) != 0ull) {
;         const float m_new = fmaxf(m_run, mx); const float m_use = (m_new == -INFINITY) ? 0.f : m_new;
;         const float alpha = __builtin_amdgcn_exp2f(m_run - m_use);
;         l_run *= alpha; m_run = m_new;
;         if (hi == 0) sc[r32] = alpha;
;         __builtin_amdgcn_fence(__ATOMIC_RELEASE, "wavefront");
;         __builtin_amdgcn_wave_barrier();
; #pragma unroll
;         for (int g4 = 0; g4 < 4; ++g4) { const f32x4 a4 = *(const f32x4*)&sc[8 * g4 + 4 * hi];
; #pragma unroll
;           for (int cb = 0; cb < NCB; ++cb)
; #pragma unroll
;             for (int j = 0; j < 4; ++j) o[cb][4 * g4 + j] *= a4[j]; }
;         __builtin_amdgcn_wave_barrier();
;       }
;       const float m_ref = (m_run == -INFINITY) ? 0.f : m_run;
;       float rs0 = 0.f, rs1 = 0.f;
; #pragma unroll
;       for (int r = 0; r < 16; ++r) { const float e0 = __builtin_amdgcn_exp2f(p0[r] - m_ref), e1 = __builtin_amdgcn_exp2f(p1[r] - m_ref); p0[r] = e0; p1[r] = e1; rs0 += e0; rs1 += e1; }
;       l_run += xhalf_sum(rs0 + rs1);
.LBB1_320:
	ds_read_b128 v[208:211], v132
	ds_read_b128 v[212:215], v132 offset:6656
	ds_read_b128 v[216:219], v132 offset:32
	ds_read_b128 v[220:223], v132 offset:6688
	ds_read_b128 v[224:227], v132 offset:64
	ds_read_b128 v[228:231], v132 offset:6720
	ds_read_b128 v[232:235], v132 offset:96
	ds_read_b128 v[236:239], v132 offset:6752
	ds_read_b128 v[240:243], v132 offset:128
	ds_read_b128 v[244:247], v132 offset:6784
	ds_read_b128 v[248:251], v132 offset:160
	ds_read_b128 v[134:137], v132 offset:6816
	s_waitcnt lgkmcnt(11)
	v_mfma_f32_32x32x16_bf16 v[34:49], v[208:211], v[66:69], v[150:165]
	s_waitcnt lgkmcnt(10)
	v_mfma_f32_32x32x16_bf16 v[50:65], v[212:215], v[66:69], v[150:165]
	s_waitcnt lgkmcnt(9)
	v_mfma_f32_32x32x16_bf16 v[34:49], v[216:219], v[70:73], v[34:49]
	s_waitcnt lgkmcnt(8)
	v_mfma_f32_32x32x16_bf16 v[50:65], v[220:223], v[70:73], v[50:65]
	s_waitcnt lgkmcnt(7)
	v_mfma_f32_32x32x16_bf16 v[34:49], v[224:227], v[74:77], v[34:49]
	s_waitcnt lgkmcnt(6)
	v_mfma_f32_32x32x16_bf16 v[50:65], v[228:231], v[74:77], v[50:65]
	s_waitcnt lgkmcnt(5)
	v_mfma_f32_32x32x16_bf16 v[34:49], v[232:235], v[78:81], v[34:49]
	s_waitcnt lgkmcnt(4)
	v_mfma_f32_32x32x16_bf16 v[50:65], v[236:239], v[78:81], v[50:65]
	s_waitcnt lgkmcnt(3)
	v_mfma_f32_32x32x16_bf16 v[34:49], v[240:243], v[82:85], v[34:49]
	s_waitcnt lgkmcnt(2)
	v_mfma_f32_32x32x16_bf16 v[50:65], v[244:247], v[82:85], v[50:65]
	s_waitcnt lgkmcnt(1)
	v_mfma_f32_32x32x16_bf16 v[34:49], v[248:251], v[86:89], v[34:49]
	s_waitcnt lgkmcnt(0)
	v_mfma_f32_32x32x16_bf16 v[50:65], v[134:137], v[86:89], v[50:65]
	ds_read2_b64 v[208:211], v166 offset0:128 offset1:130
	ds_read2_b64 v[212:215], v167 offset0:160 offset1:162
	ds_read2_b64 v[216:219], v166 offset0:136 offset1:138
	ds_read2_b64 v[220:223], v167 offset0:168 offset1:170
	ds_read2_b64 v[224:227], v166 offset0:132 offset1:134
	ds_read2_b64 v[228:231], v167 offset0:164 offset1:166
	ds_read2_b64 v[232:235], v166 offset0:140 offset1:142
	ds_read2_b64 v[236:239], v167 offset0:172 offset1:174
	s_cbranch_scc1 .Lmla_nold
	global_load_dwordx4 v[106:109], v118, s[14:15]
	global_load_dwordx4 v[98:101], v116, s[14:15]
	global_load_dwordx4 v[102:105], v114, s[14:15]
	global_load_dwordx4 v[90:93], v110, s[12:13]
	global_load_dwordx4 v[94:97], v112, s[12:13]
	s_branch .Lmla_ld
.Lmla_nold:
	s_nop 3
.Lmla_ld:
	v_max3_f32 v0, v34, v50, v35
	v_max3_f32 v134, v51, v36, v52
	v_max3_f32 v0, v0, v37, v53
	v_max3_f32 v134, v134, v38, v54
	v_max3_f32 v0, v0, v39, v55
	v_max3_f32 v134, v134, v40, v56
	v_max3_f32 v0, v0, v41, v57
	v_max3_f32 v134, v134, v42, v58
	v_max3_f32 v0, v0, v43, v59
	v_max3_f32 v134, v134, v44, v60
	v_max3_f32 v0, v0, v45, v61
	v_max3_f32 v134, v134, v46, v62
	v_max3_f32 v0, v0, v47, v63
	v_max3_f32 v134, v134, v48, v64
	v_max3_f32 v0, v0, v49, v65
	v_max_f32_e32 v0, v0, v134
	v_mov_b32_e32 v134, v0
	s_nop 1
	v_permlane32_swap_b32_e32 v0, v134
	v_max_f32_e32 v0, v0, v134
	v_sub_f32_e32 v0, v0, v150
	v_add_f32_e32 v134, 0x41000000, v133
	v_cmp_gt_f32_e32 vcc, v0, v134
	s_cbranch_vccz .LBB1_324
	v_max_f32_e32 v0, v0, v0
	v_max_f32_e32 v134, v133, v133
	v_max_f32_e32 v0, v134, v0
	v_cmp_neq_f32_e32 vcc, s7, v0
	s_nop 1
	v_cndmask_b32_e32 v134, 0, v0, vcc
	v_sub_f32_e32 v133, v133, v134
	v_exp_f32_e32 v133, v133
	v_add_f32_e32 v168, v150, v134
	s_and_saveexec_b64 s[22:23], s[36:37]
	ds_write_b32 v124, v133 offset:34816
	s_or_b64 exec, exec, s[22:23]
	s_waitcnt lgkmcnt(0)
	ds_read_b128 v[136:139], v120 offset:34816
	ds_read_b128 v[140:143], v120 offset:34848
	ds_read_b128 v[144:147], v120 offset:34880
	ds_read_b128 v[240:243], v120 offset:34912
	v_mul_f32_e32 v126, v126, v133
	v_sub_f32_e32 v34, v34, v168
	v_sub_f32_e32 v35, v35, v168
	v_sub_f32_e32 v36, v36, v168
	v_sub_f32_e32 v37, v37, v168
	v_sub_f32_e32 v38, v38, v168
	v_sub_f32_e32 v39, v39, v168
	v_sub_f32_e32 v40, v40, v168
	v_sub_f32_e32 v41, v41, v168
	v_sub_f32_e32 v42, v42, v168
	v_sub_f32_e32 v43, v43, v168
	v_sub_f32_e32 v44, v44, v168
	v_sub_f32_e32 v45, v45, v168
	v_sub_f32_e32 v46, v46, v168
	v_sub_f32_e32 v47, v47, v168
	v_sub_f32_e32 v48, v48, v168
	v_sub_f32_e32 v49, v49, v168
	v_sub_f32_e32 v50, v50, v168
	v_sub_f32_e32 v51, v51, v168
	v_sub_f32_e32 v52, v52, v168
	v_sub_f32_e32 v53, v53, v168
	v_sub_f32_e32 v54, v54, v168
	v_sub_f32_e32 v55, v55, v168
	v_sub_f32_e32 v56, v56, v168
	v_sub_f32_e32 v57, v57, v168
	v_sub_f32_e32 v58, v58, v168
	v_sub_f32_e32 v59, v59, v168
	v_sub_f32_e32 v60, v60, v168
	v_sub_f32_e32 v61, v61, v168
	v_sub_f32_e32 v62, v62, v168
	v_sub_f32_e32 v63, v63, v168
	v_sub_f32_e32 v64, v64, v168
	v_sub_f32_e32 v65, v65, v168
	v_sub_f32_e32 v150, 0, v134
	v_mov_b32_e32 v151, v150
	v_mov_b32_e32 v152, v150
	v_mov_b32_e32 v153, v150
	v_mov_b32_e32 v154, v150
	v_mov_b32_e32 v155, v150
	v_mov_b32_e32 v156, v150
	v_mov_b32_e32 v157, v150
	v_mov_b32_e32 v158, v150
	v_mov_b32_e32 v159, v150
	v_mov_b32_e32 v160, v150
	v_mov_b32_e32 v161, v150
	v_mov_b32_e32 v162, v150
	v_mov_b32_e32 v163, v150
	v_mov_b32_e32 v164, v150
	v_mov_b32_e32 v165, v150
	s_waitcnt lgkmcnt(0)
	v_pk_mul_f32 v[2:3], v[2:3], v[136:137]
	v_pk_mul_f32 v[4:5], v[4:5], v[138:139]
	v_pk_mul_f32 v[6:7], v[6:7], v[140:141]
	v_pk_mul_f32 v[8:9], v[8:9], v[142:143]
	v_pk_mul_f32 v[10:11], v[10:11], v[144:145]
	v_pk_mul_f32 v[12:13], v[12:13], v[146:147]
	v_pk_mul_f32 v[14:15], v[14:15], v[240:241]
	v_pk_mul_f32 v[16:17], v[16:17], v[242:243]
	v_pk_mul_f32 v[18:19], v[18:19], v[136:137]
	v_pk_mul_f32 v[20:21], v[20:21], v[138:139]
	v_pk_mul_f32 v[22:23], v[22:23], v[140:141]
	v_pk_mul_f32 v[24:25], v[24:25], v[142:143]
	v_pk_mul_f32 v[26:27], v[26:27], v[144:145]
	v_pk_mul_f32 v[28:29], v[28:29], v[146:147]
	v_pk_mul_f32 v[30:31], v[30:31], v[240:241]
	v_pk_mul_f32 v[32:33], v[32:33], v[242:243]
	s_branch .LBB1_325
